# P4 sample-rows out-proj+RMSNorm spread over all 256 WGs (16 row groups x 16 col slices, K split over waves, sc1 row-sum exchange) instead of 16 WGs
# speedup vs baseline: 1.0442x; 1.0442x over previous
.LBB0_885:
	s_add_i32 s71, s70, 0xffffff90
	s_lshl_b32 s0, s71, 8
	s_and_b32 s3, s0, 0x7800
	s_lshr_b32 s0, s71, 1
	s_and_b32 s2, s0, 0x7fffffc0
	s_lshl_b32 s0, s70, 3
	s_and_b32 s0, s0, 56
	s_or_b32 s0, s0, 0x7c0
	v_readlane_b32 s4, v254, 51
	v_mov_b32_e32 v43, v132
	s_sub_i32 s0, s0, s2
	v_readlane_b32 s5, v254, 52
	s_mov_b32 s1, s5
	v_ashrrev_i32_e32 v42, 6, v43
	s_or_b32 s0, s0, s3
	v_and_b32_e32 v2, -4, v42
	v_ashrrev_i32_e32 v3, 31, v2
	v_writelane_b32 v254, s0, 51
	s_waitcnt lgkmcnt(0)
	v_lshrrev_b32_e32 v1, 1, v43
	s_waitcnt vmcnt(0)
	v_and_b32_e32 v4, 2, v1
	v_writelane_b32 v254, s1, 52
	v_lshl_add_u64 v[2:3], v[2:3], 0, s[0:1]
	v_bfe_u32 v5, v43, 4, 1
	v_and_b32_e32 v6, 3, v43
	v_or3_b32 v4, v4, v5, v2
	v_mov_b32_e32 v5, v3
	v_readlane_b32 s4, v254, 1
	v_bfe_u32 v0, v43, 5, 1
	v_and_or_b32 v1, v1, 4, v6
	v_lshlrev_b64 v[4:5], 9, v[4:5]
	v_readlane_b32 s8, v254, 5
	v_readlane_b32 s9, v254, 6
	v_lshlrev_b32_e32 v16, 6, v1
	v_lshl_or_b32 v2, v0, 1, v2
	v_lshl_add_u64 v[4:5], s[8:9], 0, v[4:5]
	v_readlane_b32 s12, v254, 9
	v_readlane_b32 s13, v254, 10
	v_lshl_add_u64 v[4:5], v[4:5], 0, v[16:17]
	v_lshlrev_b32_e32 v16, 4, v0
	v_lshlrev_b64 v[2:3], 5, v[2:3]
	v_lshl_add_u64 v[4:5], v[4:5], 0, v[16:17]
	v_lshl_add_u64 v[2:3], s[12:13], 0, v[2:3]
	global_load_dwordx4 v[18:21], v[4:5], off
	global_load_dwordx4 v[22:25], v[4:5], off offset:32
	global_load_dwordx4 v[26:29], v[2:3], off offset:48
	global_load_dwordx4 v[30:33], v[2:3], off offset:32
	global_load_dwordx4 v[34:37], v[2:3], off offset:16
	global_load_dwordx4 v[38:41], v[2:3], off
	v_readlane_b32 s6, v254, 3
	s_sub_i32 s72, 0x800, s2
	s_movk_i32 s0, 0xff
	v_and_b32_e32 v47, 3, v42
	v_cmp_lt_u32_e32 vcc, s0, v43
	s_lshr_b32 s6, s72, 5
	v_readlane_b32 s5, v254, 2
	v_cndmask_b32_e32 v46, 0, v77, vcc
	v_cmp_gt_u32_e32 vcc, s6, v47
	v_readlane_b32 s7, v254, 4
	v_readlane_b32 s10, v254, 7
	v_readlane_b32 s11, v254, 8
	v_readlane_b32 s14, v254, 11
	v_readlane_b32 s15, v254, 12
	v_readlane_b32 s16, v254, 13
	v_readlane_b32 s17, v254, 14
	v_readlane_b32 s18, v254, 15
	v_readlane_b32 s19, v254, 16
	s_barrier
	s_and_saveexec_b64 s[0:1], vcc
	s_cbranch_execz .LBB0_890
	v_readlane_b32 s8, v254, 1
	v_and_b32_e32 v1, 31, v43
	v_lshlrev_b32_e32 v2, 3, v0
	s_lshl_b32 s3, s3, 6
	v_readlane_b32 s14, v254, 7
	v_readlane_b32 s15, v254, 8
	s_add_u32 s4, s14, s3
	v_mul_u32_u24_e32 v0, 0x8200, v0
	v_lshlrev_b32_e32 v16, 1, v2
	v_lshlrev_b32_e32 v2, 7, v47
	v_lshlrev_b32_e32 v3, 2, v1
	s_addc_u32 s5, s15, 0
	v_or3_b32 v0, v0, v2, v3
	s_sub_i32 s7, 0x7ff, s2
	v_lshl_add_u64 v[44:45], s[4:5], 0, v[16:17]
	v_add_u32_e32 v48, v46, v0
	v_lshl_or_b32 v49, v47, 5, v1
	s_mov_b64 s[2:3], 0
	v_mov_b32_e32 v50, v47
	v_readlane_b32 s9, v254, 2
	v_readlane_b32 s10, v254, 3
	v_readlane_b32 s11, v254, 4
	v_readlane_b32 s12, v254, 5
	v_readlane_b32 s13, v254, 6
	v_readlane_b32 s16, v254, 9
	v_readlane_b32 s17, v254, 10
	v_readlane_b32 s18, v254, 11
	v_readlane_b32 s19, v254, 12
	v_readlane_b32 s20, v254, 13
	v_readlane_b32 s21, v254, 14
	v_readlane_b32 s22, v254, 15
	v_readlane_b32 s23, v254, 16
	s_branch .LBB0_888
.LBB0_887:
	s_or_b64 exec, exec, s[4:5]
	v_add_u32_e32 v50, 4, v50
	v_cmp_le_u32_e32 vcc, s6, v50
	v_add_u32_e32 v48, 0x200, v48
	s_or_b64 s[2:3], vcc, s[2:3]
	v_add_u32_e32 v49, 0x80, v49
	s_andn2_b64 exec, exec, s[2:3]
	s_cbranch_execz .LBB0_890
.LBB0_888:
	s_nop 1
	v_min_u32_e32 v0, s7, v49
	v_lshlrev_b32_e32 v16, 6, v0
	v_lshl_add_u64 v[52:53], v[44:45], 0, v[16:17]
	global_load_dwordx4 v[0:3], v[52:53], off
	v_cmp_gt_u32_e32 vcc, s72, v49
	global_load_dwordx4 v[52:55], v[52:53], off offset:32
	s_waitcnt vmcnt(1)
	v_mfma_f32_32x32x16_bf16 v[0:15], v[18:21], v[0:3], 0
	s_waitcnt vmcnt(0)
	v_mfma_f32_32x32x16_bf16 v[0:15], v[22:25], v[52:55], v[0:15]
	s_and_saveexec_b64 s[4:5], vcc
	s_cbranch_execz .LBB0_887
	s_nop 9
	v_max_f32_e32 v0, v0, v0
	v_max_f32_e32 v1, v1, v1
	v_max_f32_e32 v8, v8, v8
	v_max_f32_e32 v9, v9, v9
	v_max_f32_e32 v0, 0, v0
	v_max_f32_e32 v1, 0, v1
	v_max_f32_e32 v8, 0, v8
	v_max_f32_e32 v9, 0, v9
	v_pk_mul_f32 v[0:1], v[38:39], v[0:1]
	v_max_f32_e32 v2, v2, v2
	v_max_f32_e32 v3, v3, v3
	v_pk_mul_f32 v[8:9], v[30:31], v[8:9]
	v_max_f32_e32 v10, v10, v10
	v_max_f32_e32 v11, v11, v11
	v_max_f32_e32 v2, 0, v2
	v_max_f32_e32 v3, 0, v3
	v_max_f32_e32 v10, 0, v10
	v_max_f32_e32 v11, 0, v11
	v_mov_b32_e32 v52, v8
	v_mov_b32_e32 v53, v0
	v_pk_mul_f32 v[2:3], v[40:41], v[2:3]
	v_max_f32_e32 v4, v4, v4
	v_max_f32_e32 v5, v5, v5
	v_pk_mul_f32 v[10:11], v[32:33], v[10:11]
	v_max_f32_e32 v12, v12, v12
	v_max_f32_e32 v13, v13, v13
	v_pk_add_f32 v[52:53], v[52:53], 0 op_sel_hi:[1,0]
	v_mov_b32_e32 v0, v9
	v_max_f32_e32 v4, 0, v4
	v_max_f32_e32 v5, 0, v5
	v_max_f32_e32 v12, 0, v12
	v_max_f32_e32 v13, 0, v13
	v_pk_add_f32 v[0:1], v[0:1], v[52:53]
	v_mov_b32_e32 v8, v10
	v_mov_b32_e32 v9, v2
	v_pk_mul_f32 v[4:5], v[34:35], v[4:5]
	v_max_f32_e32 v6, v6, v6
	v_max_f32_e32 v7, v7, v7
	v_pk_mul_f32 v[12:13], v[26:27], v[12:13]
	v_max_f32_e32 v14, v14, v14
	v_max_f32_e32 v15, v15, v15
	v_pk_add_f32 v[0:1], v[8:9], v[0:1]
	v_mov_b32_e32 v2, v11
	v_max_f32_e32 v6, 0, v6
	v_max_f32_e32 v7, 0, v7
	v_max_f32_e32 v14, 0, v14
	v_max_f32_e32 v15, 0, v15
	v_pk_add_f32 v[0:1], v[2:3], v[0:1]
	v_mov_b32_e32 v2, v12
	v_mov_b32_e32 v3, v4
	v_pk_mul_f32 v[6:7], v[36:37], v[6:7]
	v_pk_mul_f32 v[14:15], v[28:29], v[14:15]
	v_pk_add_f32 v[0:1], v[2:3], v[0:1]
	v_mov_b32_e32 v4, v13
	v_pk_add_f32 v[0:1], v[4:5], v[0:1]
	v_mov_b32_e32 v2, v14
	v_mov_b32_e32 v3, v6
	v_pk_add_f32 v[0:1], v[2:3], v[0:1]
	v_mov_b32_e32 v6, v15
	v_pk_add_f32 v[0:1], v[6:7], v[0:1]
	s_nop 0
	v_or_b32_e32 v2, 0x80000000, v1
	v_not_b32_e32 v3, v1
	v_cmp_gt_i32_e32 vcc, 0, v1
	s_nop 1
	v_cndmask_b32_e32 v1, v2, v3, vcc
	v_or_b32_e32 v2, 0x80000000, v0
	v_not_b32_e32 v3, v0
	v_cmp_gt_i32_e32 vcc, 0, v0
	s_nop 1
	v_cndmask_b32_e32 v0, v2, v3, vcc
	ds_write2st64_b32 v48, v1, v0 offset1:65
	s_branch .LBB0_887

.LBB0_1807:
	s_waitcnt lgkmcnt(0)
	s_barrier
	s_cmp_lt_u32 s48, 0x100
	s_cbranch_scc0 .LBB0_1815
	s_load_dwordx2 s[0:1], s[60:61], 0x1b0
	s_load_dwordx2 s[2:3], s[60:61], 0xa0
	s_load_dwordx2 s[4:5], s[60:61], 0x8
	s_load_dwordx4 s[8:11], s[60:61], 0x80
	s_load_dwordx2 s[12:13], s[60:61], 0xb0
	s_load_dwordx2 s[14:15], s[60:61], 0x1c0
	s_and_b32 s16, s48, 15
	s_lshr_b32 s17, s48, 4
	v_lshrrev_b32_e32 v0, 6, v132
	v_and_b32_e32 v1, 63, v132
	v_and_b32_e32 v2, 15, v1
	v_lshrrev_b32_e32 v3, 4, v1
	v_lshlrev_b32_e32 v5, 6, v132
	v_readfirstlane_b32 s18, v0
	v_lshlrev_b32_e32 v4, 11, v2
	v_lshl_add_u32 v4, v3, 4, v4
	v_lshlrev_b32_e32 v6, 14, v3
	v_lshl_add_u32 v6, v2, 4, v6
	v_add_u32_e32 v124, 0x1000, v6
	v_add_u32_e32 v125, 0x2000, v6
	v_add_u32_e32 v126, 0x3000, v6
	v_lshlrev_b32_e32 v127, 4, v2
	v_lshlrev_b32_e32 v7, 4, v3
	v_lshl_add_u32 v10, v2, 6, v7
	s_lshl_b32 s29, s17, 6
	v_add_u32_e32 v7, s29, v7
	v_mov_b32_e32 v9, 0
	v_mov_b32_e32 v11, 1
	s_lshl_b32 s19, s18, 8
	s_waitcnt lgkmcnt(0)
	s_lshl_b32 s20, s16, 15
	s_add_u32 s20, s20, s19
	s_add_u32 s0, s0, s20
	s_addc_u32 s1, s1, 0
	s_lshl_b32 s20, s17, 17
	s_add_u32 s20, s20, s19
	s_add_u32 s2, s2, s20
	s_addc_u32 s3, s3, 0
	s_add_u32 s22, s2, 0x8000
	s_addc_u32 s23, s3, 0
	s_add_u32 s24, s2, 0x10000
	s_addc_u32 s25, s3, 0
	s_add_u32 s26, s2, 0x18000
	s_addc_u32 s27, s3, 0
	s_lshl_b32 s20, s16, 16
	s_lshl_b32 s21, s17, 8
	s_add_u32 s20, s20, s21
	s_add_u32 s4, s4, s20
	s_addc_u32 s5, s5, 0
	s_add_u32 s10, s10, s20
	s_addc_u32 s11, s11, 0
	s_add_u32 s10, s10, 0x8000000
	s_addc_u32 s11, s11, 0
	s_add_u32 s8, s8, s21
	s_addc_u32 s9, s9, 0
	s_lshl_b32 s20, s16, 10
	s_add_u32 s12, s12, s20
	s_addc_u32 s13, s13, 0
	s_lshl_b32 s20, s16, 2
	s_add_u32 s20, s20, 0x200
	s_add_u32 s14, s14, s20
	s_addc_u32 s15, s15, 0
	global_load_dwordx4 v[104:107], v4, s[0:1]
	global_load_dwordx4 v[24:27], v4, s[2:3]
	global_load_dwordx4 v[40:43], v4, s[22:23]
	global_load_dwordx4 v[56:59], v4, s[24:25]
	global_load_dwordx4 v[72:75], v4, s[26:27]
	global_load_dwordx4 v[108:111], v4, s[0:1] offset:64
	global_load_dwordx4 v[28:31], v4, s[2:3] offset:64
	global_load_dwordx4 v[44:47], v4, s[22:23] offset:64
	global_load_dwordx4 v[60:63], v4, s[24:25] offset:64
	global_load_dwordx4 v[76:79], v4, s[26:27] offset:64
	global_load_dwordx4 v[112:115], v4, s[0:1] offset:128
	global_load_dwordx4 v[32:35], v4, s[2:3] offset:128
	global_load_dwordx4 v[48:51], v4, s[22:23] offset:128
	global_load_dwordx4 v[64:67], v4, s[24:25] offset:128
	global_load_dwordx4 v[80:83], v4, s[26:27] offset:128
	global_load_dwordx4 v[116:119], v4, s[0:1] offset:192
	global_load_dwordx4 v[36:39], v4, s[2:3] offset:192
	global_load_dwordx4 v[52:55], v4, s[22:23] offset:192
	global_load_dwordx4 v[68:71], v4, s[24:25] offset:192
	global_load_dwordx4 v[84:87], v4, s[26:27] offset:192
	s_waitcnt vmcnt(0)
	v_mfma_f32_16x16x32_bf16 v[88:91], v[104:107], v[24:27], 0
	v_mfma_f32_16x16x32_bf16 v[92:95], v[104:107], v[40:43], 0
	v_mfma_f32_16x16x32_bf16 v[96:99], v[104:107], v[56:59], 0
	v_mfma_f32_16x16x32_bf16 v[100:103], v[104:107], v[72:75], 0
	v_mfma_f32_16x16x32_bf16 v[88:91], v[108:111], v[28:31], v[88:91]
	v_mfma_f32_16x16x32_bf16 v[92:95], v[108:111], v[44:47], v[92:95]
	v_mfma_f32_16x16x32_bf16 v[96:99], v[108:111], v[60:63], v[96:99]
	v_mfma_f32_16x16x32_bf16 v[100:103], v[108:111], v[76:79], v[100:103]
	v_mfma_f32_16x16x32_bf16 v[88:91], v[112:115], v[32:35], v[88:91]
	v_mfma_f32_16x16x32_bf16 v[92:95], v[112:115], v[48:51], v[92:95]
	v_mfma_f32_16x16x32_bf16 v[96:99], v[112:115], v[64:67], v[96:99]
	v_mfma_f32_16x16x32_bf16 v[100:103], v[112:115], v[80:83], v[100:103]
	v_mfma_f32_16x16x32_bf16 v[88:91], v[116:119], v[36:39], v[88:91]
	v_mfma_f32_16x16x32_bf16 v[92:95], v[116:119], v[52:55], v[92:95]
	v_mfma_f32_16x16x32_bf16 v[96:99], v[116:119], v[68:71], v[96:99]
	v_mfma_f32_16x16x32_bf16 v[100:103], v[116:119], v[84:87], v[100:103]
	s_nop 7
	s_nop 3
	ds_write_b128 v5, v[88:91]
	ds_write_b128 v5, v[92:95] offset:16
	ds_write_b128 v5, v[96:99] offset:32
	ds_write_b128 v5, v[100:103] offset:48
	s_waitcnt lgkmcnt(0)
	s_barrier
	s_cmp_lg_u32 s18, 0
	s_cbranch_scc1 .LBB0_1815
	global_load_dwordx4 v[104:107], v6, s[4:5]
	global_load_dwordx4 v[108:111], v124, s[4:5]
	global_load_dwordx4 v[112:115], v125, s[4:5]
	global_load_dwordx4 v[116:119], v126, s[4:5]
	global_load_dwordx4 v[120:123], v127, s[8:9]
	ds_read_b128 v[24:27], v5 offset:4096
	ds_read_b128 v[28:31], v5 offset:4112
	ds_read_b128 v[32:35], v5 offset:4128
	ds_read_b128 v[36:39], v5 offset:4144
	ds_read_b128 v[40:43], v5 offset:8192
	ds_read_b128 v[44:47], v5 offset:8208
	ds_read_b128 v[48:51], v5 offset:8224
	ds_read_b128 v[52:55], v5 offset:8240
	ds_read_b128 v[56:59], v5 offset:12288
	ds_read_b128 v[60:63], v5 offset:12304
	ds_read_b128 v[64:67], v5 offset:12320
	ds_read_b128 v[68:71], v5 offset:12336
	ds_read_b128 v[72:75], v5 offset:16384
	ds_read_b128 v[76:79], v5 offset:16400
	ds_read_b128 v[80:83], v5 offset:16416
	ds_read_b128 v[84:87], v5 offset:16432
	s_waitcnt lgkmcnt(0)
	v_add_f32_e32 v88, v88, v24
	v_add_f32_e32 v89, v89, v25
	v_add_f32_e32 v90, v90, v26
	v_add_f32_e32 v91, v91, v27
	v_add_f32_e32 v92, v92, v28
	v_add_f32_e32 v93, v93, v29
	v_add_f32_e32 v94, v94, v30
	v_add_f32_e32 v95, v95, v31
	v_add_f32_e32 v96, v96, v32
	v_add_f32_e32 v97, v97, v33
	v_add_f32_e32 v98, v98, v34
	v_add_f32_e32 v99, v99, v35
	v_add_f32_e32 v100, v100, v36
	v_add_f32_e32 v101, v101, v37
	v_add_f32_e32 v102, v102, v38
	v_add_f32_e32 v103, v103, v39
	v_add_f32_e32 v88, v88, v40
	v_add_f32_e32 v89, v89, v41
	v_add_f32_e32 v90, v90, v42
	v_add_f32_e32 v91, v91, v43
	v_add_f32_e32 v92, v92, v44
	v_add_f32_e32 v93, v93, v45
	v_add_f32_e32 v94, v94, v46
	v_add_f32_e32 v95, v95, v47
	v_add_f32_e32 v96, v96, v48
	v_add_f32_e32 v97, v97, v49
	v_add_f32_e32 v98, v98, v50
	v_add_f32_e32 v99, v99, v51
	v_add_f32_e32 v100, v100, v52
	v_add_f32_e32 v101, v101, v53
	v_add_f32_e32 v102, v102, v54
	v_add_f32_e32 v103, v103, v55
	v_add_f32_e32 v88, v88, v56
	v_add_f32_e32 v89, v89, v57
	v_add_f32_e32 v90, v90, v58
	v_add_f32_e32 v91, v91, v59
	v_add_f32_e32 v92, v92, v60
	v_add_f32_e32 v93, v93, v61
	v_add_f32_e32 v94, v94, v62
	v_add_f32_e32 v95, v95, v63
	v_add_f32_e32 v96, v96, v64
	v_add_f32_e32 v97, v97, v65
	v_add_f32_e32 v98, v98, v66
	v_add_f32_e32 v99, v99, v67
	v_add_f32_e32 v100, v100, v68
	v_add_f32_e32 v101, v101, v69
	v_add_f32_e32 v102, v102, v70
	v_add_f32_e32 v103, v103, v71
	v_add_f32_e32 v88, v88, v72
	v_add_f32_e32 v89, v89, v73
	v_add_f32_e32 v90, v90, v74
	v_add_f32_e32 v91, v91, v75
	v_add_f32_e32 v92, v92, v76
	v_add_f32_e32 v93, v93, v77
	v_add_f32_e32 v94, v94, v78
	v_add_f32_e32 v95, v95, v79
	v_add_f32_e32 v96, v96, v80
	v_add_f32_e32 v97, v97, v81
	v_add_f32_e32 v98, v98, v82
	v_add_f32_e32 v99, v99, v83
	v_add_f32_e32 v100, v100, v84
	v_add_f32_e32 v101, v101, v85
	v_add_f32_e32 v102, v102, v86
	v_add_f32_e32 v103, v103, v87
	ds_read_b128 v[24:27], v5 offset:20480
	ds_read_b128 v[28:31], v5 offset:20496
	ds_read_b128 v[32:35], v5 offset:20512
	ds_read_b128 v[36:39], v5 offset:20528
	ds_read_b128 v[40:43], v5 offset:24576
	ds_read_b128 v[44:47], v5 offset:24592
	ds_read_b128 v[48:51], v5 offset:24608
	ds_read_b128 v[52:55], v5 offset:24624
	ds_read_b128 v[56:59], v5 offset:28672
	ds_read_b128 v[60:63], v5 offset:28688
	ds_read_b128 v[64:67], v5 offset:28704
	ds_read_b128 v[68:71], v5 offset:28720
	s_waitcnt lgkmcnt(0)
	v_add_f32_e32 v88, v88, v24
	v_add_f32_e32 v89, v89, v25
	v_add_f32_e32 v90, v90, v26
	v_add_f32_e32 v91, v91, v27
	v_add_f32_e32 v92, v92, v28
	v_add_f32_e32 v93, v93, v29
	v_add_f32_e32 v94, v94, v30
	v_add_f32_e32 v95, v95, v31
	v_add_f32_e32 v96, v96, v32
	v_add_f32_e32 v97, v97, v33
	v_add_f32_e32 v98, v98, v34
	v_add_f32_e32 v99, v99, v35
	v_add_f32_e32 v100, v100, v36
	v_add_f32_e32 v101, v101, v37
	v_add_f32_e32 v102, v102, v38
	v_add_f32_e32 v103, v103, v39
	v_add_f32_e32 v88, v88, v40
	v_add_f32_e32 v89, v89, v41
	v_add_f32_e32 v90, v90, v42
	v_add_f32_e32 v91, v91, v43
	v_add_f32_e32 v92, v92, v44
	v_add_f32_e32 v93, v93, v45
	v_add_f32_e32 v94, v94, v46
	v_add_f32_e32 v95, v95, v47
	v_add_f32_e32 v96, v96, v48
	v_add_f32_e32 v97, v97, v49
	v_add_f32_e32 v98, v98, v50
	v_add_f32_e32 v99, v99, v51
	v_add_f32_e32 v100, v100, v52
	v_add_f32_e32 v101, v101, v53
	v_add_f32_e32 v102, v102, v54
	v_add_f32_e32 v103, v103, v55
	v_add_f32_e32 v88, v88, v56
	v_add_f32_e32 v89, v89, v57
	v_add_f32_e32 v90, v90, v58
	v_add_f32_e32 v91, v91, v59
	v_add_f32_e32 v92, v92, v60
	v_add_f32_e32 v93, v93, v61
	v_add_f32_e32 v94, v94, v62
	v_add_f32_e32 v95, v95, v63
	v_add_f32_e32 v96, v96, v64
	v_add_f32_e32 v97, v97, v65
	v_add_f32_e32 v98, v98, v66
	v_add_f32_e32 v99, v99, v67
	v_add_f32_e32 v100, v100, v68
	v_add_f32_e32 v101, v101, v69
	v_add_f32_e32 v102, v102, v70
	v_add_f32_e32 v103, v103, v71
	s_waitcnt vmcnt(0)
	v_add_f32_e32 v88, v88, v104
	v_add_f32_e32 v89, v89, v108
	v_add_f32_e32 v90, v90, v112
	v_add_f32_e32 v91, v91, v116
	v_add_f32_e32 v92, v92, v105
	v_add_f32_e32 v93, v93, v109
	v_add_f32_e32 v94, v94, v113
	v_add_f32_e32 v95, v95, v117
	v_add_f32_e32 v96, v96, v106
	v_add_f32_e32 v97, v97, v110
	v_add_f32_e32 v98, v98, v114
	v_add_f32_e32 v99, v99, v118
	v_add_f32_e32 v100, v100, v107
	v_add_f32_e32 v101, v101, v111
	v_add_f32_e32 v102, v102, v115
	v_add_f32_e32 v103, v103, v119
	v_mul_f32_e32 v128, v88, v88
	v_mul_f32_e32 v129, v89, v89
	v_mul_f32_e32 v130, v90, v90
	v_mul_f32_e32 v131, v91, v91
	v_fmac_f32_e32 v128, v92, v92
	v_fmac_f32_e32 v129, v93, v93
	v_fmac_f32_e32 v130, v94, v94
	v_fmac_f32_e32 v131, v95, v95
	v_fmac_f32_e32 v128, v96, v96
	v_fmac_f32_e32 v129, v97, v97
	v_fmac_f32_e32 v130, v98, v98
	v_fmac_f32_e32 v131, v99, v99
	v_fmac_f32_e32 v128, v100, v100
	v_fmac_f32_e32 v129, v101, v101
	v_fmac_f32_e32 v130, v102, v102
	v_fmac_f32_e32 v131, v103, v103
	s_nop 1
	v_add_f32_dpp v128, v128, v128 quad_perm:[1,0,3,2] row_mask:0xf bank_mask:0xf
	v_add_f32_dpp v129, v129, v129 quad_perm:[1,0,3,2] row_mask:0xf bank_mask:0xf
	v_add_f32_dpp v130, v130, v130 quad_perm:[1,0,3,2] row_mask:0xf bank_mask:0xf
	v_add_f32_dpp v131, v131, v131 quad_perm:[1,0,3,2] row_mask:0xf bank_mask:0xf
	s_nop 1
	v_add_f32_dpp v128, v128, v128 quad_perm:[2,3,0,1] row_mask:0xf bank_mask:0xf
	v_add_f32_dpp v129, v129, v129 quad_perm:[2,3,0,1] row_mask:0xf bank_mask:0xf
	v_add_f32_dpp v130, v130, v130 quad_perm:[2,3,0,1] row_mask:0xf bank_mask:0xf
	v_add_f32_dpp v131, v131, v131 quad_perm:[2,3,0,1] row_mask:0xf bank_mask:0xf
	s_nop 1
	v_add_f32_dpp v128, v128, v128 row_half_mirror row_mask:0xf bank_mask:0xf
	v_add_f32_dpp v129, v129, v129 row_half_mirror row_mask:0xf bank_mask:0xf
	v_add_f32_dpp v130, v130, v130 row_half_mirror row_mask:0xf bank_mask:0xf
	v_add_f32_dpp v131, v131, v131 row_half_mirror row_mask:0xf bank_mask:0xf
	s_nop 1
	v_add_f32_dpp v128, v128, v128 row_mirror row_mask:0xf bank_mask:0xf
	v_add_f32_dpp v129, v129, v129 row_mirror row_mask:0xf bank_mask:0xf
	v_add_f32_dpp v130, v130, v130 row_mirror row_mask:0xf bank_mask:0xf
	v_add_f32_dpp v131, v131, v131 row_mirror row_mask:0xf bank_mask:0xf
	v_cmp_eq_u32_e32 vcc, 0, v2
	s_nop 1
	s_and_saveexec_b64 s[28:29], vcc
	global_store_dwordx4 v7, v[128:131], s[12:13] sc1
	s_or_b64 exec, exec, s[28:29]
	s_waitcnt vmcnt(0)
	v_cmp_eq_u32_e32 vcc, 0, v1
	s_nop 1
	s_and_saveexec_b64 s[28:29], vcc
	global_atomic_add v9, v11, s[14:15]
	s_or_b64 exec, exec, s[28:29]
	s_mov_b32 s30, 0
.Lsmp_spin:
	global_load_dword v8, v9, s[14:15] sc1
	s_waitcnt vmcnt(0)
	v_readfirstlane_b32 s31, v8
	s_nop 3
	s_cmp_ge_u32 s31, 16
	s_cbranch_scc1 .Lsmp_go
	s_sleep 1
	s_add_u32 s30, s30, 1
	s_cmp_lt_u32 s30, 0x400000
	s_cbranch_scc1 .Lsmp_spin
.Lsmp_go:
	global_load_dwordx4 v[12:15], v10, s[12:13] sc1
	v_mov_b32_e32 v16, 0x358637bd
	s_waitcnt vmcnt(0)
	s_nop 1
	v_add_f32_dpp v12, v12, v12 quad_perm:[1,0,3,2] row_mask:0xf bank_mask:0xf
	v_add_f32_dpp v13, v13, v13 quad_perm:[1,0,3,2] row_mask:0xf bank_mask:0xf
	v_add_f32_dpp v14, v14, v14 quad_perm:[1,0,3,2] row_mask:0xf bank_mask:0xf
	v_add_f32_dpp v15, v15, v15 quad_perm:[1,0,3,2] row_mask:0xf bank_mask:0xf
	s_nop 1
	v_add_f32_dpp v12, v12, v12 quad_perm:[2,3,0,1] row_mask:0xf bank_mask:0xf
	v_add_f32_dpp v13, v13, v13 quad_perm:[2,3,0,1] row_mask:0xf bank_mask:0xf
	v_add_f32_dpp v14, v14, v14 quad_perm:[2,3,0,1] row_mask:0xf bank_mask:0xf
	v_add_f32_dpp v15, v15, v15 quad_perm:[2,3,0,1] row_mask:0xf bank_mask:0xf
	s_nop 1
	v_add_f32_dpp v12, v12, v12 row_half_mirror row_mask:0xf bank_mask:0xf
	v_add_f32_dpp v13, v13, v13 row_half_mirror row_mask:0xf bank_mask:0xf
	v_add_f32_dpp v14, v14, v14 row_half_mirror row_mask:0xf bank_mask:0xf
	v_add_f32_dpp v15, v15, v15 row_half_mirror row_mask:0xf bank_mask:0xf
	s_nop 1
	v_add_f32_dpp v12, v12, v12 row_mirror row_mask:0xf bank_mask:0xf
	v_add_f32_dpp v13, v13, v13 row_mirror row_mask:0xf bank_mask:0xf
	v_add_f32_dpp v14, v14, v14 row_mirror row_mask:0xf bank_mask:0xf
	v_add_f32_dpp v15, v15, v15 row_mirror row_mask:0xf bank_mask:0xf
	v_fmamk_f32 v12, v12, 0x3a800000, v16
	v_fmamk_f32 v13, v13, 0x3a800000, v16
	v_fmamk_f32 v14, v14, 0x3a800000, v16
	v_fmamk_f32 v15, v15, 0x3a800000, v16
	v_rsq_f32_e32 v12, v12
	v_rsq_f32_e32 v13, v13
	v_rsq_f32_e32 v14, v14
	v_rsq_f32_e32 v15, v15
	s_nop 0
	v_mul_f32_e32 v24, v88, v12
	v_mul_f32_e32 v25, v92, v12
	v_mul_f32_e32 v26, v96, v12
	v_mul_f32_e32 v27, v100, v12
	v_mul_f32_e32 v28, v89, v13
	v_mul_f32_e32 v29, v93, v13
	v_mul_f32_e32 v30, v97, v13
	v_mul_f32_e32 v31, v101, v13
	v_mul_f32_e32 v32, v90, v14
	v_mul_f32_e32 v33, v94, v14
	v_mul_f32_e32 v34, v98, v14
	v_mul_f32_e32 v35, v102, v14
	v_mul_f32_e32 v36, v91, v15
	v_mul_f32_e32 v37, v95, v15
	v_mul_f32_e32 v38, v99, v15
	v_mul_f32_e32 v39, v103, v15
	v_mul_f32_e32 v24, v24, v120
	v_mul_f32_e32 v25, v25, v121
	v_mul_f32_e32 v26, v26, v122
	v_mul_f32_e32 v27, v27, v123
	v_mul_f32_e32 v28, v28, v120
	v_mul_f32_e32 v29, v29, v121
	v_mul_f32_e32 v30, v30, v122
	v_mul_f32_e32 v31, v31, v123
	v_mul_f32_e32 v32, v32, v120
	v_mul_f32_e32 v33, v33, v121
	v_mul_f32_e32 v34, v34, v122
	v_mul_f32_e32 v35, v35, v123
	v_mul_f32_e32 v36, v36, v120
	v_mul_f32_e32 v37, v37, v121
	v_mul_f32_e32 v38, v38, v122
	v_mul_f32_e32 v39, v39, v123
	global_store_dwordx4 v6, v[24:27], s[10:11]
	global_store_dwordx4 v124, v[28:31], s[10:11]
	global_store_dwordx4 v125, v[32:35], s[10:11]
	global_store_dwordx4 v126, v[36:39], s[10:11]
